# leader L2 write-back dropped at seams 2 and 8 (no cross-XCD consumer of P2/P8 outputs)
# speedup vs baseline: 1.0310x; 1.0050x over previous
; __device__ __forceinline__ unsigned xb_add(unsigned* p, unsigned v) { return __hip_atomic_fetch_add(p, v, __ATOMIC_RELAXED, __HIP_MEMORY_SCOPE_AGENT); }
; __device__ __forceinline__ void xcd_barrier(const XcdBarrier& b) {
;     ...
;         const unsigned old = xb_add(&bar[XB_XSUB(b.x)], 1u);
;         const unsigned gen = old / nloc;
;         if (old + 1u == (gen + 1u) * nloc) {
;             __builtin_amdgcn_fence(__ATOMIC_RELEASE, "agent");
;             asm volatile("s_waitcnt vmcnt(0)" ::: "memory");
;             const unsigned og = xb_add(&bar[XB_TOP], 1u);
;             const unsigned tg = og / nx;
;             if (og + 1u == (tg + 1u) * nx) xb_add(&bar[XB_TOPGEN], 1u);
.LBB0_386:
	s_andn2_saveexec_b64 s[8:9], s[8:9]
	s_cbranch_execz .LBB0_406
	s_mov_b64 s[8:9], exec
	s_waitcnt lgkmcnt(0)
	s_waitcnt vmcnt(0)
	v_mbcnt_lo_u32_b32 v2, s8, 0
	v_mbcnt_hi_u32_b32 v2, s9, v2
	v_cmp_eq_u32_e32 vcc, 0, v2
	s_and_saveexec_b64 s[10:11], vcc
	s_cbranch_execz .LBB0_389
	s_bcnt1_i32_b64 s8, s[8:9]
	v_mov_b32_e32 v3, 0xfd03000
	v_mov_b32_e32 v4, s8
	global_atomic_add v3, v3, v4, s[66:67] offset:1024 sc0

; __device__ __forceinline__ unsigned xb_add(unsigned* p, unsigned v) { return __hip_atomic_fetch_add(p, v, __ATOMIC_RELAXED, __HIP_MEMORY_SCOPE_AGENT); }
; __device__ __forceinline__ void xcd_barrier(const XcdBarrier& b) {
;     ...
;         const unsigned old = xb_add(&bar[XB_XSUB(b.x)], 1u);
;         const unsigned gen = old / nloc;
;         if (old + 1u == (gen + 1u) * nloc) {
;             __builtin_amdgcn_fence(__ATOMIC_RELEASE, "agent");
;             asm volatile("s_waitcnt vmcnt(0)" ::: "memory");
;             const unsigned og = xb_add(&bar[XB_TOP], 1u);
;             const unsigned tg = og / nx;
;             if (og + 1u == (tg + 1u) * nx) xb_add(&bar[XB_TOPGEN], 1u);
.LBB0_1171:
	s_andn2_saveexec_b64 s[6:7], s[6:7]
	s_cbranch_execz .LBB0_1191
	s_mov_b64 s[6:7], exec
	s_waitcnt lgkmcnt(0)
	s_waitcnt vmcnt(0)
	v_mbcnt_lo_u32_b32 v2, s6, 0
	v_mbcnt_hi_u32_b32 v2, s7, v2
	v_cmp_eq_u32_e32 vcc, 0, v2
	s_and_saveexec_b64 s[8:9], vcc
	s_cbranch_execz .LBB0_1174
	s_bcnt1_i32_b64 s6, s[6:7]
	v_mov_b32_e32 v3, 0xfd03000
	v_mov_b32_e32 v4, s6
	global_atomic_add v3, v3, v4, s[66:67] offset:1024 sc0
